# flat->global + per-XCD tile queues hand out 4-tile patches (1 m-tile x 4 n-tiles) instead of 64-tile patches
# speedup vs baseline: 1.0329x; 1.0049x over previous
; DI int TID() { int t = threadIdx.x; asm volatile("" : "+v"(t)); return t; }
; DI void phase_gemm(const Params& p, int g, int kind, char* smem, float* rsl, int* s_item, int vlo, int vhi, int cslot) {
;     ...
;   auto fetch = [&](TD& d) {
;     for (;;) {
;       __syncthreads();
;       if (TID() == 0) *s_item = atomicAdd(qctr, 1);
;       __syncthreads();
;       const int kq = *s_item;
;       const int tile = ((kq >> 6) * 8 + xcd) * 64 + (kq & 63);
;       if (tile >= total) { d.ok = false; return; }
;       const int strip = tile / (MT * 8), rem = tile - strip * (MT * 8);
;       const int wdt = min(8, nvt - strip * 8);
;       const int mt = rem / wdt, vt = vlo + strip * 8 + rem % wdt;
;       d.nt = kind == 0 ? nt_map0(vt) : vt; d.m0 = mt * 128; d.n0 = d.nt * 256;
;       if (kind == 0) { d.A = (const bfu*)(G + L0_H) + (long)d.m0 * 2048; d.Bt = P_WA + (long)d.n0 * 2048; d.K = 2048; }
.LBB0_187:
	s_or_b64 exec, exec, s[2:3]
	v_mov_b32_e32 v0, 0x122d0
	s_waitcnt lgkmcnt(0)
	s_barrier
	ds_read_b32 v0, v0
	s_waitcnt lgkmcnt(0)
	v_readfirstlane_b32 s2, v0
	s_lshr_b32 s3, s2, 2
	s_lshl_b32 s3, s3, 3
	s_or_b32 s3, s3, s33
	s_and_b32 s2, s2, 3
	s_lshl_b32 s3, s3, 2
	s_or_b32 s2, s3, s2
	s_cmpk_lt_i32 s2, 0x3f0
	s_cselect_b64 s[4:5], -1, 0
	s_cmpk_gt_i32 s2, 0x3ef
	s_cbranch_scc1 .LBB0_189
	s_mul_hi_i32 s3, s2, 0x38e38e39
	s_lshr_b32 s6, s3, 31
	s_ashr_i32 s3, s3, 6
	s_add_i32 s3, s3, s6
	s_lshl_b32 s6, s3, 3
	s_sub_i32 s7, 28, s6
	s_min_u32 s7, s7, 8
	v_cvt_f32_ubyte0_e32 v0, s7
	v_rcp_iflag_f32_e32 v0, v0
	s_sub_i32 s9, 0, s7
	s_mulk_i32 s3, 0xfee0
	s_add_i32 s3, s3, s2
	v_mul_f32_e32 v0, 0x4f7ffffe, v0
	v_cvt_u32_f32_e32 v0, v0
	s_abs_i32 s8, s3
	s_ashr_i32 s2, s3, 31
	v_readfirstlane_b32 s10, v0
	s_mul_i32 s9, s9, s10
	s_mul_hi_u32 s9, s10, s9
	s_add_i32 s10, s10, s9
	s_mul_hi_u32 s9, s8, s10
	s_mul_i32 s10, s9, s7
	s_sub_i32 s8, s8, s10
	s_add_i32 s10, s9, 1
	s_sub_i32 s11, s8, s7
	s_cmp_ge_u32 s8, s7
	s_cselect_b32 s9, s10, s9
	s_cselect_b32 s8, s11, s8
	s_add_i32 s10, s9, 1
	s_cmp_ge_u32 s8, s7
	s_cselect_b32 s8, s10, s9
	s_xor_b32 s8, s8, s2
	s_sub_i32 s2, s8, s2
	s_mul_i32 s7, s2, s7
	s_sub_i32 s3, s3, s7
	s_add_i32 s3, s3, s6
	s_add_i32 s6, s3, 24
	s_sub_i32 s7, s3, 17
	s_cmp_lg_u32 s3, 16
	s_cselect_b32 s7, s7, 64
	s_cmp_lt_i32 s3, 16
	s_cselect_b32 s94, s6, s7
	s_lshl_b32 s30, s2, 7
	s_ashr_i32 s31, s30, 31
	s_lshl_b32 s34, s94, 8
	s_lshl_b64 s[2:3], s[30:31], 12
	s_add_u32 s2, s0, s2
	s_addc_u32 s3, s1, s3
	s_add_u32 s36, s2, 0xea00000
	s_addc_u32 s37, s3, 0
	s_ashr_i32 s35, s34, 31
	s_lshl_b64 s[2:3], s[34:35], 12
	v_readlane_b32 s6, v254, 13
	s_add_u32 s38, s6, s2
	v_readlane_b32 s2, v254, 14
	s_addc_u32 s39, s2, s3
	v_cndmask_b32_e64 v0, 0, 1, s[4:5]
	v_cmp_ne_u32_e64 s[2:3], 1, v0
	s_andn2_b64 vcc, exec, s[4:5]
	s_cbranch_vccnz .LBB0_191
	s_branch .LBB0_190

; DI int TID() { int t = threadIdx.x; asm volatile("" : "+v"(t)); return t; }
; DI void phase_gemm(const Params& p, int g, int kind, char* smem, float* rsl, int* s_item, int vlo, int vhi, int cslot) {
;     ...
;   auto fetch = [&](TD& d) {
;     for (;;) {
;       __syncthreads();
;       if (TID() == 0) *s_item = atomicAdd(qctr, 1);
;       __syncthreads();
;       const int kq = *s_item;
;       const int tile = ((kq >> 6) * 8 + xcd) * 64 + (kq & 63);
;       if (tile >= total) { d.ok = false; return; }
;       const int strip = tile / (MT * 8), rem = tile - strip * (MT * 8);
;       const int wdt = min(8, nvt - strip * 8);
;       const int mt = rem / wdt, vt = vlo + strip * 8 + rem % wdt;
;       d.nt = kind == 0 ? nt_map0(vt) : vt; d.m0 = mt * 128; d.n0 = d.nt * 256;
;       if (kind == 0) { d.A = (const bfu*)(G + L0_H) + (long)d.m0 * 2048; d.Bt = P_WA + (long)d.n0 * 2048; d.K = 2048; }
.LBB0_201:
	s_or_b64 exec, exec, s[2:3]
	s_waitcnt lgkmcnt(0)
	s_barrier
	ds_read_b32 v176, v183
	s_waitcnt lgkmcnt(0)
	v_readfirstlane_b32 s1, v176
	s_lshr_b32 s2, s1, 2
	s_lshl_b32 s2, s2, 3
	s_or_b32 s2, s2, s33
	s_and_b32 s1, s1, 3
	s_lshl_b32 s2, s2, 2
	s_or_b32 s1, s2, s1
	s_cmpk_lt_i32 s1, 0x3f0
	s_cselect_b64 s[2:3], -1, 0
	s_cmpk_gt_i32 s1, 0x3ef
	s_cselect_b64 s[50:51], -1, 0
	s_and_b64 vcc, exec, s[50:51]
	s_cbranch_vccnz .LBB0_203
	s_mul_hi_i32 s4, s1, 0x38e38e39
	s_lshr_b32 s5, s4, 31
	s_ashr_i32 s4, s4, 6
	s_add_i32 s4, s4, s5
	s_lshl_b32 s5, s4, 3
	s_sub_i32 s6, 28, s5
	s_min_u32 s6, s6, 8
	v_cvt_f32_ubyte0_e32 v176, s6
	v_rcp_iflag_f32_e32 v176, v176
	s_sub_i32 s8, 0, s6
	s_mulk_i32 s4, 0xfee0
	s_add_i32 s4, s4, s1
	v_mul_f32_e32 v176, 0x4f7ffffe, v176
	v_cvt_u32_f32_e32 v176, v176
	s_abs_i32 s7, s4
	s_ashr_i32 s1, s4, 31
	v_readfirstlane_b32 s9, v176
	s_mul_i32 s8, s8, s9
	s_mul_hi_u32 s8, s9, s8
	s_add_i32 s9, s9, s8
	s_mul_hi_u32 s8, s7, s9
	s_mul_i32 s9, s8, s6
	s_sub_i32 s7, s7, s9
	s_add_i32 s9, s8, 1
	s_sub_i32 s10, s7, s6
	s_cmp_ge_u32 s7, s6
	s_cselect_b32 s8, s9, s8
	s_cselect_b32 s7, s10, s7
	s_add_i32 s9, s8, 1
	s_cmp_ge_u32 s7, s6
	s_cselect_b32 s7, s9, s8
	s_xor_b32 s7, s7, s1
	s_sub_i32 s1, s7, s1
	s_mul_i32 s6, s1, s6
	s_sub_i32 s4, s4, s6
	s_add_i32 s4, s4, s5
	s_add_i32 s5, s4, 24
	s_sub_i32 s6, s4, 17
	s_cmp_lg_u32 s4, 16
	s_cselect_b32 s6, s6, 64
	s_cmp_lt_i32 s4, 16
	s_cselect_b32 s94, s5, s6
	s_lshl_b32 s30, s1, 7
	s_ashr_i32 s31, s30, 31
	s_lshl_b32 s34, s94, 8
	s_lshl_b64 s[4:5], s[30:31], 12
	s_add_u32 s36, s61, s4
	s_addc_u32 s37, s64, s5
	s_ashr_i32 s35, s34, 31
	s_lshl_b64 s[4:5], s[34:35], 12
	v_readlane_b32 s1, v254, 13
	s_add_u32 s38, s1, s4
	v_readlane_b32 s1, v254, 14
	s_addc_u32 s39, s1, s5

; DI int TID() { int t = threadIdx.x; asm volatile("" : "+v"(t)); return t; }
; DI void phase_gemm(const Params& p, int g, int kind, char* smem, float* rsl, int* s_item, int vlo, int vhi, int cslot) {
;     ...
;   auto fetch = [&](TD& d) {
;     for (;;) {
;       __syncthreads();
;       if (TID() == 0) *s_item = atomicAdd(qctr, 1);
;       __syncthreads();
;       const int kq = *s_item;
;       const int tile = ((kq >> 6) * 8 + xcd) * 64 + (kq & 63);
;       if (tile >= total) { d.ok = false; return; }
;       const int strip = tile / (MT * 8), rem = tile - strip * (MT * 8);
;       const int wdt = min(8, nvt - strip * 8);
;       const int mt = rem / wdt, vt = vlo + strip * 8 + rem % wdt;
;       d.nt = kind == 0 ? nt_map0(vt) : vt; d.m0 = mt * 128; d.n0 = d.nt * 256;
;       if (kind == 0) { d.A = (const bfu*)(G + L0_H) + (long)d.m0 * 2048; d.Bt = P_WA + (long)d.n0 * 2048; d.K = 2048; }
.LBB0_518:
	s_or_b64 exec, exec, s[2:3]
	s_waitcnt lgkmcnt(0)
	s_barrier
	ds_read_b32 v0, v191
	s_waitcnt lgkmcnt(0)
	v_readfirstlane_b32 s2, v0
	s_lshr_b32 s3, s2, 2
	s_lshl_b32 s3, s3, 3
	s_or_b32 s3, s3, s33
	s_and_b32 s2, s2, 3
	s_lshl_b32 s3, s3, 2
	s_or_b32 s4, s3, s2
	s_cmpk_lt_i32 s4, 0x534
	s_cselect_b64 s[2:3], -1, 0
	s_cmpk_gt_i32 s4, 0x533
	s_cbranch_scc1 .LBB0_524
	s_mul_hi_i32 s5, s4, 0x38e38e39
	s_lshr_b32 s6, s5, 31
	s_ashr_i32 s5, s5, 6
	s_add_i32 s5, s5, s6
	s_lshl_b32 s7, s5, 3
	s_sub_i32 s6, 37, s7
	s_min_u32 s8, s6, 8
	v_cvt_f32_ubyte0_e32 v0, s8
	v_rcp_iflag_f32_e32 v0, v0
	s_sub_i32 s9, 0, s8
	s_mulk_i32 s5, 0xfee0
	s_add_i32 s5, s5, s4
	v_mul_f32_e32 v0, 0x4f7ffffe, v0
	v_cvt_u32_f32_e32 v0, v0
	s_abs_i32 s6, s5
	s_ashr_i32 s4, s5, 31
	v_readfirstlane_b32 s10, v0
	s_mul_i32 s9, s9, s10
	s_mul_hi_u32 s9, s10, s9
	s_add_i32 s10, s10, s9
	s_mul_hi_u32 s9, s6, s10
	s_mul_i32 s10, s9, s8
	s_sub_i32 s6, s6, s10
	s_add_i32 s10, s9, 1
	s_sub_i32 s11, s6, s8
	s_cmp_ge_u32 s6, s8
	s_cselect_b32 s9, s10, s9
	s_cselect_b32 s6, s11, s6
	s_add_i32 s10, s9, 1
	s_cmp_ge_u32 s6, s8
	s_cselect_b32 s6, s10, s9
	s_xor_b32 s6, s6, s4
	s_sub_i32 s6, s6, s4
	s_mul_i32 s4, s6, s8
	s_sub_i32 s4, s5, s4
	s_add_i32 s7, s7, s4
	s_add_i32 s7, s7, 28
	s_cmp_gt_i32 s7, 15
	s_mov_b64 s[4:5], -1
	s_cbranch_scc0 .LBB0_521
	s_cmp_lt_u32 s7, 41
	s_cselect_b32 s4, 0xffffffef, -1
	s_add_i32 s4, s4, s7
	s_cmp_lg_u32 s7, 16
	s_cselect_b32 s16, s4, 64
	s_mov_b64 s[4:5], 0

; DI int TID() { int t = threadIdx.x; asm volatile("" : "+v"(t)); return t; }
; DI void phase_gemm(const Params& p, int g, int kind, char* smem, float* rsl, int* s_item, int vlo, int vhi, int cslot) {
;     ...
;   auto fetch = [&](TD& d) {
;     for (;;) {
;       __syncthreads();
;       if (TID() == 0) *s_item = atomicAdd(qctr, 1);
;       __syncthreads();
;       const int kq = *s_item;
;       const int tile = ((kq >> 6) * 8 + xcd) * 64 + (kq & 63);
;       if (tile >= total) { d.ok = false; return; }
;       const int strip = tile / (MT * 8), rem = tile - strip * (MT * 8);
;       const int wdt = min(8, nvt - strip * 8);
;       const int mt = rem / wdt, vt = vlo + strip * 8 + rem % wdt;
;       d.nt = kind == 0 ? nt_map0(vt) : vt; d.m0 = mt * 128; d.n0 = d.nt * 256;
;       if (kind == 0) { d.A = (const bfu*)(G + L0_H) + (long)d.m0 * 2048; d.Bt = P_WA + (long)d.n0 * 2048; d.K = 2048; }
.LBB0_536:
	s_or_b64 exec, exec, s[2:3]
	s_waitcnt lgkmcnt(0)
	s_barrier
	ds_read_b32 v128, v191
	s_waitcnt lgkmcnt(0)
	v_readfirstlane_b32 s1, v128
	s_lshr_b32 s2, s1, 2
	s_lshl_b32 s2, s2, 3
	s_or_b32 s2, s2, s33
	s_and_b32 s1, s1, 3
	s_lshl_b32 s2, s2, 2
	s_or_b32 s1, s2, s1
	s_cmpk_lt_i32 s1, 0x534
	s_cselect_b64 s[2:3], -1, 0
	s_cmpk_gt_i32 s1, 0x533
	s_cselect_b64 s[46:47], -1, 0
	s_and_b64 vcc, exec, s[46:47]
	s_cbranch_vccnz .LBB0_543
	s_mul_hi_i32 s4, s1, 0x38e38e39
	s_lshr_b32 s5, s4, 31
	s_ashr_i32 s4, s4, 6
	s_add_i32 s4, s4, s5
	s_lshl_b32 s5, s4, 3
	s_sub_i32 s6, 37, s5
	s_min_u32 s6, s6, 8
	v_cvt_f32_ubyte0_e32 v128, s6
	v_rcp_iflag_f32_e32 v128, v128
	s_sub_i32 s13, 0, s6
	s_mulk_i32 s4, 0xfee0
	s_add_i32 s4, s4, s1
	v_mul_f32_e32 v128, 0x4f7ffffe, v128
	v_cvt_u32_f32_e32 v128, v128
	s_abs_i32 s7, s4
	s_ashr_i32 s1, s4, 31
	v_readfirstlane_b32 s14, v128
	s_mul_i32 s13, s13, s14
	s_mul_hi_u32 s13, s14, s13
	s_add_i32 s14, s14, s13
	s_mul_hi_u32 s13, s7, s14
	s_mul_i32 s14, s13, s6
	s_sub_i32 s7, s7, s14
	s_add_i32 s14, s13, 1
	s_sub_i32 s15, s7, s6
	s_cmp_ge_u32 s7, s6
	s_cselect_b32 s13, s14, s13
	s_cselect_b32 s7, s15, s7
	s_add_i32 s14, s13, 1
	s_cmp_ge_u32 s7, s6
	s_cselect_b32 s7, s14, s13
	s_xor_b32 s7, s7, s1
	s_sub_i32 s1, s7, s1
	s_mul_i32 s6, s1, s6
	s_sub_i32 s4, s4, s6
	s_add_i32 s6, s5, s4
	s_add_i32 s6, s6, 28
	s_cmp_gt_i32 s6, 15
	s_mov_b64 s[4:5], -1
	s_cbranch_scc0 .LBB0_539
	s_cmp_lt_u32 s6, 41
	s_cselect_b32 s4, 0xffffffef, -1
	s_add_i32 s4, s4, s6
	s_cmp_lg_u32 s6, 16
	s_cselect_b32 s16, s4, 64
	s_mov_b64 s[4:5], 0

; DI int TID() { int t = threadIdx.x; asm volatile("" : "+v"(t)); return t; }
; DI void phase_gemm(const Params& p, int g, int kind, char* smem, float* rsl, int* s_item, int vlo, int vhi, int cslot) {
;     ...
;   auto fetch = [&](TD& d) {
;     for (;;) {
;       __syncthreads();
;       if (TID() == 0) *s_item = atomicAdd(qctr, 1);
;       __syncthreads();
;       const int kq = *s_item;
;       const int tile = ((kq >> 6) * 8 + xcd) * 64 + (kq & 63);
;       if (tile >= total) { d.ok = false; return; }
;       const int strip = tile / (MT * 8), rem = tile - strip * (MT * 8);
;       const int wdt = min(8, nvt - strip * 8);
;       const int mt = rem / wdt, vt = vlo + strip * 8 + rem % wdt;
;       d.nt = kind == 0 ? nt_map0(vt) : vt; d.m0 = mt * 128; d.n0 = d.nt * 256;
;       if (kind == 0) { d.A = (const bfu*)(G + L0_H) + (long)d.m0 * 2048; d.Bt = P_WA + (long)d.n0 * 2048; d.K = 2048; }
;       else if (kind == 1) { d.A = (const bfu*)(G + L1_H) + (long)d.m0 * 2048; d.Bt = (const bfu*)((char*)P_WA + WA_W2) + (long)d.n0 * 2048; d.K = 2048; }
;       else if (kind == 2) {
;         if (d.nt < 12) { d.A = (const bfu*)(G + L1_QL) + (long)d.m0 * 512; d.Bt = (const bfu*)((char*)P_WA + WA_UQ) + (long)d.n0 * 512; d.K = 512; }
;         else { d.n0 -= 12 * 256; d.A = (const bfu*)(G + L1_KVL) + (long)d.m0 * 256; d.Bt = (const bfu*)((char*)P_WA + WA_UKV) + (long)d.n0 * 256; d.K = 256; }
;       } else {
;         const int layer = kind - 3;
;         if (layer == 1 && (d.m0 % T) < CTX) continue;
;         d.A = (const bfu*)(G + (layer == 0 ? L0_MIX : L1_MIX)) + (long)d.m0 * 4096;
;         d.Bt = (layer == 0 ? P_WO1 : (const bfu*)((char*)P_WA + WA_WO2)) + (long)d.n0 * 4096; d.K = 4096;
;       }
.LBB0_879:
	s_or_b64 exec, exec, s[0:1]
	s_waitcnt lgkmcnt(0)
	s_barrier
	ds_read_b32 v0, v191
	s_waitcnt lgkmcnt(0)
	v_readfirstlane_b32 s0, v0
	s_lshr_b32 s1, s0, 2
	s_lshl_b32 s1, s1, 3
	s_or_b32 s1, s1, s33
	s_and_b32 s0, s0, 3
	s_lshl_b32 s1, s1, 2
	s_or_b32 s1, s1, s0
	s_cmpk_lt_i32 s1, 0x120
	s_cselect_b64 s[2:3], -1, 0
	s_cmpk_gt_i32 s1, 0x11f
	s_cbranch_scc1 .LBB0_881
	s_mul_hi_i32 s0, s1, 0x38e38e39
	s_lshr_b32 s6, s0, 31
	s_ashr_i32 s0, s0, 6
	s_add_i32 s0, s0, s6
	s_mul_i32 s6, s0, 0xfffffee0
	s_add_i32 s1, s6, s1
	s_ashr_i32 s6, s1, 31
	s_lshr_b32 s6, s6, 29
	s_add_i32 s6, s1, s6
	s_and_b32 s7, s6, 0xfffff8
	s_lshl_b32 s6, s6, 4
	s_sub_i32 s1, s1, s7
	s_and_b32 s14, s6, 0xffffff80
	s_lshl_b32 s0, s0, 11
	s_lshl_b32 s1, s1, 8
	s_ashr_i32 s15, s14, 31
	s_add_i32 s0, s0, s1
	s_lshl_b64 s[6:7], s[14:15], 13
	s_add_u32 s1, s12, s6
	s_addc_u32 s6, s13, s7
	s_add_u32 s8, s1, 0xfc00000
	s_addc_u32 s9, s6, 0
	s_ashr_i32 s1, s0, 31
	s_lshl_b64 s[6:7], s[0:1], 13
	v_readlane_b32 s1, v254, 11
	s_add_u32 s10, s1, s6
	v_readlane_b32 s1, v254, 12
	s_addc_u32 s11, s1, s7

; DI int TID() { int t = threadIdx.x; asm volatile("" : "+v"(t)); return t; }
; DI void phase_gemm(const Params& p, int g, int kind, char* smem, float* rsl, int* s_item, int vlo, int vhi, int cslot) {
;     ...
;   auto fetch = [&](TD& d) {
;     for (;;) {
;       __syncthreads();
;       if (TID() == 0) *s_item = atomicAdd(qctr, 1);
;       __syncthreads();
;       const int kq = *s_item;
;       const int tile = ((kq >> 6) * 8 + xcd) * 64 + (kq & 63);
;       if (tile >= total) { d.ok = false; return; }
;       const int strip = tile / (MT * 8), rem = tile - strip * (MT * 8);
;       const int wdt = min(8, nvt - strip * 8);
;       const int mt = rem / wdt, vt = vlo + strip * 8 + rem % wdt;
;       d.nt = kind == 0 ? nt_map0(vt) : vt; d.m0 = mt * 128; d.n0 = d.nt * 256;
;       if (kind == 0) { d.A = (const bfu*)(G + L0_H) + (long)d.m0 * 2048; d.Bt = P_WA + (long)d.n0 * 2048; d.K = 2048; }
;       else if (kind == 1) { d.A = (const bfu*)(G + L1_H) + (long)d.m0 * 2048; d.Bt = (const bfu*)((char*)P_WA + WA_W2) + (long)d.n0 * 2048; d.K = 2048; }
;       else if (kind == 2) {
;         if (d.nt < 12) { d.A = (const bfu*)(G + L1_QL) + (long)d.m0 * 512; d.Bt = (const bfu*)((char*)P_WA + WA_UQ) + (long)d.n0 * 512; d.K = 512; }
;         else { d.n0 -= 12 * 256; d.A = (const bfu*)(G + L1_KVL) + (long)d.m0 * 256; d.Bt = (const bfu*)((char*)P_WA + WA_UKV) + (long)d.n0 * 256; d.K = 256; }
;       } else {
;         const int layer = kind - 3;
;         if (layer == 1 && (d.m0 % T) < CTX) continue;
;         d.A = (const bfu*)(G + (layer == 0 ? L0_MIX : L1_MIX)) + (long)d.m0 * 4096;
;         d.Bt = (layer == 0 ? P_WO1 : (const bfu*)((char*)P_WA + WA_WO2)) + (long)d.n0 * 4096; d.K = 4096;
;       }
.LBB0_892:
	s_or_b64 exec, exec, s[2:3]
	s_waitcnt lgkmcnt(0)
	s_barrier
	ds_read_b32 v128, v191
	s_waitcnt lgkmcnt(0)
	v_readfirstlane_b32 s1, v128
	s_lshr_b32 s2, s1, 2
	s_lshl_b32 s2, s2, 3
	s_or_b32 s2, s2, s33
	s_and_b32 s1, s1, 3
	s_lshl_b32 s2, s2, 2
	s_or_b32 s1, s2, s1
	s_cmpk_lt_i32 s1, 0x120
	s_cselect_b64 s[2:3], -1, 0
	s_cmpk_gt_i32 s1, 0x11f
	s_cselect_b64 s[16:17], -1, 0
	s_and_b64 vcc, exec, s[16:17]
	s_cbranch_vccnz .LBB0_894
	s_mul_hi_i32 s6, s1, 0x38e38e39
	s_lshr_b32 s7, s6, 31
	s_ashr_i32 s6, s6, 6
	s_add_i32 s7, s6, s7
	s_mul_i32 s6, s7, 0xfffffee0
	s_add_i32 s1, s6, s1
	s_ashr_i32 s6, s1, 31
	s_lshr_b32 s6, s6, 29
	s_add_i32 s6, s1, s6
	s_and_b32 s8, s6, 0xfffff8
	s_sub_i32 s1, s1, s8
	s_lshl_b32 s6, s6, 4
	s_and_b32 s6, s6, 0xffffff80
	s_lshl_b32 s7, s7, 11
	s_lshl_b32 s1, s1, 8
	s_add_i32 s12, s7, s1
	s_ashr_i32 s7, s6, 31
	s_lshl_b64 s[8:9], s[6:7], 13
	s_add_u32 s8, s26, s8
	s_addc_u32 s9, s27, s9
	s_ashr_i32 s13, s12, 31
	s_lshl_b64 s[10:11], s[12:13], 13
	v_readlane_b32 s1, v254, 11
	s_add_u32 s10, s1, s10
	v_readlane_b32 s1, v254, 12
	s_addc_u32 s11, s1, s11

; DI int TID() { int t = threadIdx.x; asm volatile("" : "+v"(t)); return t; }
; DI void phase_gemm(const Params& p, int g, int kind, char* smem, float* rsl, int* s_item, int vlo, int vhi, int cslot) {
;     ...
;   auto fetch = [&](TD& d) {
;     for (;;) {
;       __syncthreads();
;       if (TID() == 0) *s_item = atomicAdd(qctr, 1);
;       __syncthreads();
;       const int kq = *s_item;
;       const int tile = ((kq >> 6) * 8 + xcd) * 64 + (kq & 63);
;       if (tile >= total) { d.ok = false; return; }
;       const int strip = tile / (MT * 8), rem = tile - strip * (MT * 8);
;       const int wdt = min(8, nvt - strip * 8);
;       const int mt = rem / wdt, vt = vlo + strip * 8 + rem % wdt;
;       d.nt = kind == 0 ? nt_map0(vt) : vt; d.m0 = mt * 128; d.n0 = d.nt * 256;
;       if (kind == 0) { d.A = (const bfu*)(G + L0_H) + (long)d.m0 * 2048; d.Bt = P_WA + (long)d.n0 * 2048; d.K = 2048; }
.LBB0_919:
	s_or_b64 exec, exec, s[2:3]
	s_waitcnt lgkmcnt(0)
	s_barrier
	ds_read_b32 v0, v191
	v_mov_b32_e32 v242, 0xff800000
	v_mov_b32_e32 v214, 0x7fc00000
	v_mov_b32_e32 v209, 0x7f800000
	v_mov_b32_e32 v201, 0x3ecc95a3
	s_waitcnt lgkmcnt(0)
	v_readfirstlane_b32 s2, v0
	s_lshr_b32 s3, s2, 2
	s_lshl_b32 s3, s3, 3
	s_or_b32 s3, s3, s33
	s_and_b32 s2, s2, 3
	s_lshl_b32 s3, s3, 2
	s_or_b32 s4, s3, s2
	s_cmpk_lt_i32 s4, 0x3f0
	s_cselect_b64 s[2:3], -1, 0
	s_cmpk_gt_i32 s4, 0x3ef
	s_cbranch_scc1 .LBB0_921
	s_mul_hi_i32 s5, s4, 0x38e38e39
	s_lshr_b32 s6, s5, 31
	s_ashr_i32 s5, s5, 6
	s_add_i32 s5, s5, s6
	s_lshl_b32 s6, s5, 3
	s_sub_i32 s7, 28, s6
	s_min_u32 s7, s7, 8
	v_cvt_f32_ubyte0_e32 v0, s7
	v_rcp_iflag_f32_e32 v0, v0
	s_sub_i32 s9, 0, s7
	s_mulk_i32 s5, 0xfee0
	s_add_i32 s5, s5, s4
	v_mul_f32_e32 v0, 0x4f7ffffe, v0
	v_cvt_u32_f32_e32 v0, v0
	s_abs_i32 s8, s5
	s_ashr_i32 s4, s5, 31
	v_readfirstlane_b32 s10, v0
	s_mul_i32 s9, s9, s10
	s_mul_hi_u32 s9, s10, s9
	s_add_i32 s10, s10, s9
	s_mul_hi_u32 s9, s8, s10
	s_mul_i32 s10, s9, s7
	s_sub_i32 s8, s8, s10
	s_add_i32 s10, s9, 1
	s_sub_i32 s11, s8, s7
	s_cmp_ge_u32 s8, s7
	s_cselect_b32 s9, s10, s9
	s_cselect_b32 s8, s11, s8
	s_add_i32 s10, s9, 1
	s_cmp_ge_u32 s8, s7
	s_cselect_b32 s8, s10, s9
	s_xor_b32 s8, s8, s4
	s_sub_i32 s4, s8, s4
	s_mul_i32 s7, s4, s7
	s_sub_i32 s5, s5, s7
	s_add_i32 s5, s5, s6
	s_add_i32 s6, s5, 24
	s_sub_i32 s7, s5, 17
	s_cmp_lg_u32 s5, 16
	s_cselect_b32 s7, s7, 64
	s_cmp_lt_i32 s5, 16
	s_cselect_b32 s14, s6, s7
	s_lshl_b32 s38, s4, 7
	s_ashr_i32 s39, s38, 31
	s_lshl_b32 s40, s14, 8
	s_lshl_b64 s[4:5], s[38:39], 12
	s_add_u32 s4, s0, s4
	s_addc_u32 s5, s1, s5
	s_add_u32 s42, s4, 0xea00000
	s_addc_u32 s43, s5, 0
	s_ashr_i32 s41, s40, 31
	s_lshl_b64 s[4:5], s[40:41], 12
	v_readlane_b32 s6, v254, 13
	s_add_u32 s44, s6, s4
	v_readlane_b32 s4, v254, 14
	s_addc_u32 s45, s4, s5

; DI int TID() { int t = threadIdx.x; asm volatile("" : "+v"(t)); return t; }
; DI void phase_gemm(const Params& p, int g, int kind, char* smem, float* rsl, int* s_item, int vlo, int vhi, int cslot) {
;     ...
;   auto fetch = [&](TD& d) {
;     for (;;) {
;       __syncthreads();
;       if (TID() == 0) *s_item = atomicAdd(qctr, 1);
;       __syncthreads();
;       const int kq = *s_item;
;       const int tile = ((kq >> 6) * 8 + xcd) * 64 + (kq & 63);
;       if (tile >= total) { d.ok = false; return; }
;       const int strip = tile / (MT * 8), rem = tile - strip * (MT * 8);
;       const int wdt = min(8, nvt - strip * 8);
;       const int mt = rem / wdt, vt = vlo + strip * 8 + rem % wdt;
;       d.nt = kind == 0 ? nt_map0(vt) : vt; d.m0 = mt * 128; d.n0 = d.nt * 256;
;       if (kind == 0) { d.A = (const bfu*)(G + L0_H) + (long)d.m0 * 2048; d.Bt = P_WA + (long)d.n0 * 2048; d.K = 2048; }
.LBB0_933:
	s_or_b64 exec, exec, s[2:3]
	s_waitcnt lgkmcnt(0)
	s_barrier
	ds_read_b32 v128, v191
	s_waitcnt lgkmcnt(0)
	v_readfirstlane_b32 s1, v128
	s_lshr_b32 s2, s1, 2
	s_lshl_b32 s2, s2, 3
	s_or_b32 s2, s2, s33
	s_and_b32 s1, s1, 3
	s_lshl_b32 s2, s2, 2
	s_or_b32 s1, s2, s1
	s_cmpk_lt_i32 s1, 0x3f0
	s_cselect_b64 s[2:3], -1, 0
	s_cmpk_gt_i32 s1, 0x3ef
	s_cselect_b64 s[46:47], -1, 0
	s_and_b64 vcc, exec, s[46:47]
	s_cbranch_vccnz .LBB0_935
	s_mul_hi_i32 s4, s1, 0x38e38e39
	s_lshr_b32 s5, s4, 31
	s_ashr_i32 s4, s4, 6
	s_add_i32 s4, s4, s5
	s_lshl_b32 s5, s4, 3
	s_sub_i32 s6, 28, s5
	s_min_u32 s6, s6, 8
	v_cvt_f32_ubyte0_e32 v128, s6
	v_rcp_iflag_f32_e32 v128, v128
	s_sub_i32 s11, 0, s6
	s_mulk_i32 s4, 0xfee0
	s_add_i32 s4, s4, s1
	v_mul_f32_e32 v128, 0x4f7ffffe, v128
	v_cvt_u32_f32_e32 v128, v128
	s_abs_i32 s7, s4
	s_ashr_i32 s1, s4, 31
	v_readfirstlane_b32 s12, v128
	s_mul_i32 s11, s11, s12
	s_mul_hi_u32 s11, s12, s11
	s_add_i32 s12, s12, s11
	s_mul_hi_u32 s11, s7, s12
	s_mul_i32 s12, s11, s6
	s_sub_i32 s7, s7, s12
	s_add_i32 s12, s11, 1
	s_sub_i32 s13, s7, s6
	s_cmp_ge_u32 s7, s6
	s_cselect_b32 s11, s12, s11
	s_cselect_b32 s7, s13, s7
	s_add_i32 s12, s11, 1
	s_cmp_ge_u32 s7, s6
	s_cselect_b32 s7, s12, s11
	s_xor_b32 s7, s7, s1
	s_sub_i32 s1, s7, s1
	s_mul_i32 s6, s1, s6
	s_sub_i32 s4, s4, s6
	s_add_i32 s4, s4, s5
	s_add_i32 s5, s4, 24
	s_sub_i32 s6, s4, 17
	s_cmp_lg_u32 s4, 16
	s_cselect_b32 s6, s6, 64
	s_cmp_lt_i32 s4, 16
	s_cselect_b32 s14, s5, s6
	s_lshl_b32 s38, s1, 7
	s_ashr_i32 s39, s38, 31
	s_lshl_b32 s40, s14, 8
	s_lshl_b64 s[4:5], s[38:39], 12
	s_add_u32 s42, s63, s4
	s_addc_u32 s43, s54, s5
	s_ashr_i32 s41, s40, 31
	s_lshl_b64 s[4:5], s[40:41], 12
	v_readlane_b32 s1, v254, 13
	s_add_u32 s44, s1, s4
	v_readlane_b32 s1, v254, 14
	s_addc_u32 s45, s1, s5

; DI int TID() { int t = threadIdx.x; asm volatile("" : "+v"(t)); return t; }
; DI void phase_gemm(const Params& p, int g, int kind, char* smem, float* rsl, int* s_item, int vlo, int vhi, int cslot) {
;     ...
;   auto fetch = [&](TD& d) {
;     for (;;) {
;       __syncthreads();
;       if (TID() == 0) *s_item = atomicAdd(qctr, 1);
;       __syncthreads();
;       const int kq = *s_item;
;       const int tile = ((kq >> 6) * 8 + xcd) * 64 + (kq & 63);
;       if (tile >= total) { d.ok = false; return; }
;       const int strip = tile / (MT * 8), rem = tile - strip * (MT * 8);
;       const int wdt = min(8, nvt - strip * 8);
;       const int mt = rem / wdt, vt = vlo + strip * 8 + rem % wdt;
;       d.nt = kind == 0 ? nt_map0(vt) : vt; d.m0 = mt * 128; d.n0 = d.nt * 256;
;       if (kind == 0) { d.A = (const bfu*)(G + L0_H) + (long)d.m0 * 2048; d.Bt = P_WA + (long)d.n0 * 2048; d.K = 2048; }
;       else if (kind == 1) { d.A = (const bfu*)(G + L1_H) + (long)d.m0 * 2048; d.Bt = (const bfu*)((char*)P_WA + WA_W2) + (long)d.n0 * 2048; d.K = 2048; }
.LBB0_1237:
	s_or_b64 exec, exec, s[2:3]
	s_waitcnt lgkmcnt(0)
	s_barrier
	ds_read_b32 v0, v204
	s_waitcnt lgkmcnt(0)
	v_readfirstlane_b32 s2, v0
	s_lshr_b32 s3, s2, 2
	s_lshl_b32 s3, s3, 3
	s_or_b32 s3, s3, s33
	s_and_b32 s2, s2, 3
	s_lshl_b32 s3, s3, 2
	s_or_b32 s2, s3, s2
	s_cmpk_lt_i32 s2, 0x3f0
	s_cselect_b64 s[12:13], -1, 0
	s_cmpk_gt_i32 s2, 0x3ef
	s_cbranch_scc1 .LBB0_1239
	s_mul_hi_i32 s3, s2, 0x38e38e39
	s_lshr_b32 s4, s3, 31
	s_ashr_i32 s3, s3, 6
	s_add_i32 s3, s3, s4
	s_lshl_b32 s4, s3, 3
	s_sub_i32 s5, 28, s4
	s_min_u32 s5, s5, 8
	v_cvt_f32_ubyte0_e32 v0, s5
	v_rcp_iflag_f32_e32 v0, v0
	s_sub_i32 s7, 0, s5
	s_mulk_i32 s3, 0xfee0
	s_add_i32 s3, s3, s2
	v_mul_f32_e32 v0, 0x4f7ffffe, v0
	v_cvt_u32_f32_e32 v0, v0
	s_abs_i32 s6, s3
	s_ashr_i32 s2, s3, 31
	v_readfirstlane_b32 s8, v0
	s_mul_i32 s7, s7, s8
	s_mul_hi_u32 s7, s8, s7
	s_add_i32 s8, s8, s7
	s_mul_hi_u32 s7, s6, s8
	s_mul_i32 s8, s7, s5
	s_sub_i32 s6, s6, s8
	s_add_i32 s8, s7, 1
	s_sub_i32 s9, s6, s5
	s_cmp_ge_u32 s6, s5
	s_cselect_b32 s7, s8, s7
	s_cselect_b32 s6, s9, s6
	s_add_i32 s8, s7, 1
	s_cmp_ge_u32 s6, s5
	s_cselect_b32 s6, s8, s7
	s_xor_b32 s6, s6, s2
	s_sub_i32 s2, s6, s2
	s_mul_i32 s5, s2, s5
	s_sub_i32 s3, s3, s5
	s_add_i32 s3, s3, s4
	s_lshl_b32 s4, s2, 7
	s_ashr_i32 s5, s4, 31
	s_lshl_b32 s6, s3, 8
	s_lshl_b64 s[2:3], s[4:5], 12
	s_add_u32 s2, s0, s2
	s_addc_u32 s3, s1, s3
	s_add_u32 s8, s2, 0xb400000
	s_addc_u32 s9, s3, 0
	s_ashr_i32 s7, s6, 31
	s_lshl_b64 s[2:3], s[6:7], 12
	v_readlane_b32 s5, v254, 13
	s_add_u32 s10, s5, s2
	v_readlane_b32 s2, v254, 14
	s_addc_u32 s11, s2, s3

; DI int TID() { int t = threadIdx.x; asm volatile("" : "+v"(t)); return t; }
; DI void phase_gemm(const Params& p, int g, int kind, char* smem, float* rsl, int* s_item, int vlo, int vhi, int cslot) {
;     ...
;       __syncthreads();
;       if (TID() == 0) *s_item = atomicAdd(qctr, 1);
;       __syncthreads();
;       const int kq = *s_item;
;       const int tile = ((kq >> 6) * 8 + xcd) * 64 + (kq & 63);
;       if (tile >= total) { d.ok = false; return; }
;       const int strip = tile / (MT * 8), rem = tile - strip * (MT * 8);
;       const int wdt = min(8, nvt - strip * 8);
;       const int mt = rem / wdt, vt = vlo + strip * 8 + rem % wdt;
;       d.nt = kind == 0 ? nt_map0(vt) : vt; d.m0 = mt * 128; d.n0 = d.nt * 256;
;       if (kind == 0) { d.A = (const bfu*)(G + L0_H) + (long)d.m0 * 2048; d.Bt = P_WA + (long)d.n0 * 2048; d.K = 2048; }
;       else if (kind == 1) { d.A = (const bfu*)(G + L1_H) + (long)d.m0 * 2048; d.Bt = (const bfu*)((char*)P_WA + WA_W2) + (long)d.n0 * 2048; d.K = 2048; }
.LBB0_1251:
	s_or_b64 exec, exec, s[0:1]
	s_waitcnt lgkmcnt(0)
	s_barrier
	ds_read_b32 v176, v204
	s_waitcnt lgkmcnt(0)
	v_readfirstlane_b32 s0, v176
	s_lshr_b32 s1, s0, 2
	s_lshl_b32 s1, s1, 3
	s_or_b32 s1, s1, s33
	s_and_b32 s0, s0, 3
	s_lshl_b32 s1, s1, 2
	s_or_b32 s2, s1, s0
	s_cmpk_lt_i32 s2, 0x3f0
	s_cselect_b64 s[0:1], -1, 0
	s_cmpk_gt_i32 s2, 0x3ef
	s_cselect_b64 s[16:17], -1, 0
	s_and_b64 vcc, exec, s[16:17]
	s_cbranch_vccnz .LBB0_1253
	s_mul_hi_i32 s3, s2, 0x38e38e39
	s_lshr_b32 s4, s3, 31
	s_ashr_i32 s3, s3, 6
	s_add_i32 s3, s3, s4
	s_lshl_b32 s4, s3, 3
	s_sub_i32 s5, 28, s4
	s_min_u32 s5, s5, 8
	v_cvt_f32_ubyte0_e32 v176, s5
	v_rcp_iflag_f32_e32 v176, v176
	s_sub_i32 s7, 0, s5
	s_mulk_i32 s3, 0xfee0
	s_add_i32 s3, s3, s2
	v_mul_f32_e32 v176, 0x4f7ffffe, v176
	v_cvt_u32_f32_e32 v176, v176
	s_abs_i32 s6, s3
	s_ashr_i32 s2, s3, 31
	v_readfirstlane_b32 s8, v176
	s_mul_i32 s7, s7, s8
	s_mul_hi_u32 s7, s8, s7
	s_add_i32 s8, s8, s7
	s_mul_hi_u32 s7, s6, s8
	s_mul_i32 s8, s7, s5
	s_sub_i32 s6, s6, s8
	s_add_i32 s8, s7, 1
	s_sub_i32 s9, s6, s5
	s_cmp_ge_u32 s6, s5
	s_cselect_b32 s7, s8, s7
	s_cselect_b32 s6, s9, s6
	s_add_i32 s8, s7, 1
	s_cmp_ge_u32 s6, s5
	s_cselect_b32 s6, s8, s7
	s_xor_b32 s6, s6, s2
	s_sub_i32 s2, s6, s2
	s_mul_i32 s5, s2, s5
	s_sub_i32 s3, s3, s5
	s_add_i32 s3, s3, s4
	s_lshl_b32 s4, s2, 7
	s_ashr_i32 s5, s4, 31
	s_lshl_b32 s6, s3, 8
	s_lshl_b64 s[2:3], s[4:5], 12
	s_add_u32 s8, s38, s2
	s_addc_u32 s9, s39, s3
	s_ashr_i32 s7, s6, 31
	s_lshl_b64 s[2:3], s[6:7], 12
	v_readlane_b32 s5, v254, 13
	s_add_u32 s10, s5, s2
	v_readlane_b32 s2, v254, 14
	s_addc_u32 s11, s2, s3

; DI int TID() { int t = threadIdx.x; asm volatile("" : "+v"(t)); return t; }
; DI void phase_gemm(const Params& p, int g, int kind, char* smem, float* rsl, int* s_item, int vlo, int vhi, int cslot) {
;     ...
;       __syncthreads();
;       if (TID() == 0) *s_item = atomicAdd(qctr, 1);
;       __syncthreads();
;       const int kq = *s_item;
;       const int tile = ((kq >> 6) * 8 + xcd) * 64 + (kq & 63);
;       if (tile >= total) { d.ok = false; return; }
;       const int strip = tile / (MT * 8), rem = tile - strip * (MT * 8);
;       const int wdt = min(8, nvt - strip * 8);
;       const int mt = rem / wdt, vt = vlo + strip * 8 + rem % wdt;
;       d.nt = kind == 0 ? nt_map0(vt) : vt; d.m0 = mt * 128; d.n0 = d.nt * 256;
;       if (kind == 0) { d.A = (const bfu*)(G + L0_H) + (long)d.m0 * 2048; d.Bt = P_WA + (long)d.n0 * 2048; d.K = 2048; }
;       else if (kind == 1) { d.A = (const bfu*)(G + L1_H) + (long)d.m0 * 2048; d.Bt = (const bfu*)((char*)P_WA + WA_W2) + (long)d.n0 * 2048; d.K = 2048; }
.LBB0_1559:
	s_or_b64 exec, exec, s[2:3]
	s_waitcnt lgkmcnt(0)
	s_barrier
	ds_read_b32 v0, v204
	s_waitcnt lgkmcnt(0)
	v_readfirstlane_b32 s2, v0
	s_lshr_b32 s3, s2, 2
	s_lshl_b32 s3, s3, 3
	s_or_b32 s3, s3, s33
	s_and_b32 s2, s2, 3
	s_lshl_b32 s3, s3, 2
	s_or_b32 s2, s3, s2
	s_cmpk_lt_i32 s2, 0x240
	s_cselect_b64 s[12:13], -1, 0
	s_cmpk_gt_i32 s2, 0x23f
	s_cbranch_scc1 .LBB0_1561
	s_mul_hi_i32 s3, s2, 0x38e38e39
	s_lshr_b32 s4, s3, 31
	s_ashr_i32 s3, s3, 6
	s_add_i32 s3, s3, s4
	s_mul_i32 s4, s3, 0xfffffee0
	s_add_i32 s2, s4, s2
	s_ashr_i32 s4, s2, 31
	s_lshr_b32 s4, s4, 29
	s_add_i32 s4, s2, s4
	s_and_b32 s5, s4, -8
	s_lshl_b32 s3, s3, 3
	s_sub_i32 s2, s2, s5
	s_add_i32 s2, s3, s2
	s_add_i32 s38, s2, 28
	s_lshl_b32 s2, s4, 4
	s_and_b32 s4, s2, 0xffffff80
	s_ashr_i32 s5, s4, 31
	s_lshl_b32 s6, s38, 8
	s_lshl_b64 s[2:3], s[4:5], 12
	s_add_u32 s2, s0, s2
	s_addc_u32 s3, s1, s3
	s_add_u32 s8, s2, 0xb400000
	s_addc_u32 s9, s3, 0
	s_ashr_i32 s7, s6, 31
	s_lshl_b64 s[2:3], s[6:7], 12
	v_readlane_b32 s5, v254, 13
	s_add_u32 s10, s5, s2
	v_readlane_b32 s2, v254, 14
	s_addc_u32 s11, s2, s3

; DI int TID() { int t = threadIdx.x; asm volatile("" : "+v"(t)); return t; }
; DI void phase_gemm(const Params& p, int g, int kind, char* smem, float* rsl, int* s_item, int vlo, int vhi, int cslot) {
;     ...
;       __syncthreads();
;       if (TID() == 0) *s_item = atomicAdd(qctr, 1);
;       __syncthreads();
;       const int kq = *s_item;
;       const int tile = ((kq >> 6) * 8 + xcd) * 64 + (kq & 63);
;       if (tile >= total) { d.ok = false; return; }
;       const int strip = tile / (MT * 8), rem = tile - strip * (MT * 8);
;       const int wdt = min(8, nvt - strip * 8);
;       const int mt = rem / wdt, vt = vlo + strip * 8 + rem % wdt;
;       d.nt = kind == 0 ? nt_map0(vt) : vt; d.m0 = mt * 128; d.n0 = d.nt * 256;
;       if (kind == 0) { d.A = (const bfu*)(G + L0_H) + (long)d.m0 * 2048; d.Bt = P_WA + (long)d.n0 * 2048; d.K = 2048; }
;       else if (kind == 1) { d.A = (const bfu*)(G + L1_H) + (long)d.m0 * 2048; d.Bt = (const bfu*)((char*)P_WA + WA_W2) + (long)d.n0 * 2048; d.K = 2048; }
.LBB0_1573:
	s_or_b64 exec, exec, s[0:1]
	s_waitcnt lgkmcnt(0)
	s_barrier
	ds_read_b32 v176, v204
	s_waitcnt lgkmcnt(0)
	v_readfirstlane_b32 s0, v176
	s_lshr_b32 s1, s0, 2
	s_lshl_b32 s1, s1, 3
	s_or_b32 s1, s1, s33
	s_and_b32 s0, s0, 3
	s_lshl_b32 s1, s1, 2
	s_or_b32 s2, s1, s0
	s_cmpk_lt_i32 s2, 0x240
	s_cselect_b64 s[0:1], -1, 0
	s_cmpk_gt_i32 s2, 0x23f
	s_cselect_b64 s[16:17], -1, 0
	s_and_b64 vcc, exec, s[16:17]
	s_cbranch_vccnz .LBB0_1575
	s_mul_hi_i32 s3, s2, 0x38e38e39
	s_lshr_b32 s4, s3, 31
	s_ashr_i32 s3, s3, 6
	s_add_i32 s3, s3, s4
	s_mul_i32 s4, s3, 0xfffffee0
	s_add_i32 s2, s4, s2
	s_ashr_i32 s4, s2, 31
	s_lshr_b32 s4, s4, 29
	s_add_i32 s4, s2, s4
	s_and_b32 s5, s4, -8
	s_lshl_b32 s3, s3, 3
	s_sub_i32 s2, s2, s5
	s_add_i32 s2, s3, s2
	s_add_i32 s38, s2, 28
	s_lshl_b32 s2, s4, 4
	s_and_b32 s4, s2, 0xffffff80
	s_ashr_i32 s5, s4, 31
	s_lshl_b32 s6, s38, 8
	s_lshl_b64 s[2:3], s[4:5], 12
	s_add_u32 s8, s39, s2
	s_addc_u32 s9, s40, s3
	s_ashr_i32 s7, s6, 31
	s_lshl_b64 s[2:3], s[6:7], 12
	v_readlane_b32 s5, v254, 13
	s_add_u32 s10, s5, s2
	v_readlane_b32 s2, v254, 14
	s_addc_u32 s11, s2, s3

; DI int TID() { int t = threadIdx.x; asm volatile("" : "+v"(t)); return t; }
; DI void phase_gemm(const Params& p, int g, int kind, char* smem, float* rsl, int* s_item, int vlo, int vhi, int cslot) {
;     ...
;       __syncthreads();
;       if (TID() == 0) *s_item = atomicAdd(qctr, 1);
;       __syncthreads();
;       const int kq = *s_item;
;       const int tile = ((kq >> 6) * 8 + xcd) * 64 + (kq & 63);
;       if (tile >= total) { d.ok = false; return; }
;       const int strip = tile / (MT * 8), rem = tile - strip * (MT * 8);
;       const int wdt = min(8, nvt - strip * 8);
;       const int mt = rem / wdt, vt = vlo + strip * 8 + rem % wdt;
;       d.nt = kind == 0 ? nt_map0(vt) : vt; d.m0 = mt * 128; d.n0 = d.nt * 256;
;       if (kind == 0) { d.A = (const bfu*)(G + L0_H) + (long)d.m0 * 2048; d.Bt = P_WA + (long)d.n0 * 2048; d.K = 2048; }
;       else if (kind == 1) { d.A = (const bfu*)(G + L1_H) + (long)d.m0 * 2048; d.Bt = (const bfu*)((char*)P_WA + WA_W2) + (long)d.n0 * 2048; d.K = 2048; }
;       else if (kind == 2) {
;         if (d.nt < 12) { d.A = (const bfu*)(G + L1_QL) + (long)d.m0 * 512; d.Bt = (const bfu*)((char*)P_WA + WA_UQ) + (long)d.n0 * 512; d.K = 512; }
;         else { d.n0 -= 12 * 256; d.A = (const bfu*)(G + L1_KVL) + (long)d.m0 * 256; d.Bt = (const bfu*)((char*)P_WA + WA_UKV) + (long)d.n0 * 256; d.K = 256; }
.LBB0_1729:
	s_or_b64 exec, exec, s[2:3]
	s_waitcnt lgkmcnt(0)
	s_barrier
	ds_read_b32 v0, v204
	s_waitcnt lgkmcnt(0)
	v_readfirstlane_b32 s2, v0
	s_lshr_b32 s3, s2, 2
	s_lshl_b32 s3, s3, 3
	s_or_b32 s3, s3, s33
	s_and_b32 s2, s2, 3
	s_lshl_b32 s3, s3, 2
	s_or_b32 s2, s3, s2
	s_cmpk_lt_i32 s2, 0x3f0
	s_cselect_b64 s[14:15], -1, 0
	s_cmpk_gt_i32 s2, 0x3ef
	s_cbranch_scc1 .LBB0_1734
	s_mul_hi_i32 s3, s2, 0x38e38e39
	s_lshr_b32 s4, s3, 31
	s_ashr_i32 s3, s3, 6
	s_add_i32 s3, s3, s4
	s_lshl_b32 s4, s3, 3
	s_sub_i32 s5, 28, s4
	s_min_u32 s6, s5, 8
	v_cvt_f32_ubyte0_e32 v0, s6
	v_rcp_iflag_f32_e32 v0, v0
	s_sub_i32 s7, 0, s6
	s_mulk_i32 s3, 0xfee0
	s_add_i32 s3, s3, s2
	v_mul_f32_e32 v0, 0x4f7ffffe, v0
	v_cvt_u32_f32_e32 v0, v0
	s_abs_i32 s5, s3
	s_ashr_i32 s2, s3, 31
	v_readfirstlane_b32 s8, v0
	s_mul_i32 s7, s7, s8
	s_mul_hi_u32 s7, s8, s7
	s_add_i32 s8, s8, s7
	s_mul_hi_u32 s7, s5, s8
	s_mul_i32 s8, s7, s6
	s_sub_i32 s5, s5, s8
	s_add_i32 s8, s7, 1
	s_sub_i32 s9, s5, s6
	s_cmp_ge_u32 s5, s6
	s_cselect_b32 s7, s8, s7
	s_cselect_b32 s5, s9, s5
	s_add_i32 s8, s7, 1
	s_cmp_ge_u32 s5, s6
	s_cselect_b32 s5, s8, s7
	s_xor_b32 s5, s5, s2
	s_sub_i32 s5, s5, s2
	s_mul_i32 s2, s5, s6
	s_sub_i32 s2, s3, s2
	s_add_i32 s40, s2, s4
	s_lshl_b32 s4, s40, 8
	s_cmp_lt_i32 s40, 12
	s_cbranch_scc1 .LBB0_1732
	s_addk_i32 s4, 0xf400
	s_movk_i32 s6, 0x100
	s_mov_b64 s[12:13], 0xce80000
	s_mov_b64 s[2:3], 9
	s_mov_b64 s[10:11], 0x11280000
	s_branch .LBB0_1733

; DI int TID() { int t = threadIdx.x; asm volatile("" : "+v"(t)); return t; }
; DI void phase_gemm(const Params& p, int g, int kind, char* smem, float* rsl, int* s_item, int vlo, int vhi, int cslot) {
;     ...
;       __syncthreads();
;       if (TID() == 0) *s_item = atomicAdd(qctr, 1);
;       __syncthreads();
;       const int kq = *s_item;
;       const int tile = ((kq >> 6) * 8 + xcd) * 64 + (kq & 63);
;       if (tile >= total) { d.ok = false; return; }
;       const int strip = tile / (MT * 8), rem = tile - strip * (MT * 8);
;       const int wdt = min(8, nvt - strip * 8);
;       const int mt = rem / wdt, vt = vlo + strip * 8 + rem % wdt;
;       d.nt = kind == 0 ? nt_map0(vt) : vt; d.m0 = mt * 128; d.n0 = d.nt * 256;
;       if (kind == 0) { d.A = (const bfu*)(G + L0_H) + (long)d.m0 * 2048; d.Bt = P_WA + (long)d.n0 * 2048; d.K = 2048; }
;       else if (kind == 1) { d.A = (const bfu*)(G + L1_H) + (long)d.m0 * 2048; d.Bt = (const bfu*)((char*)P_WA + WA_W2) + (long)d.n0 * 2048; d.K = 2048; }
;       else if (kind == 2) {
;         if (d.nt < 12) { d.A = (const bfu*)(G + L1_QL) + (long)d.m0 * 512; d.Bt = (const bfu*)((char*)P_WA + WA_UQ) + (long)d.n0 * 512; d.K = 512; }
;         else { d.n0 -= 12 * 256; d.A = (const bfu*)(G + L1_KVL) + (long)d.m0 * 256; d.Bt = (const bfu*)((char*)P_WA + WA_UKV) + (long)d.n0 * 256; d.K = 256; }
.LBB0_1754:
	s_or_b64 exec, exec, s[2:3]
	s_waitcnt lgkmcnt(0)
	s_barrier
	ds_read_b32 v176, v204
	s_waitcnt lgkmcnt(0)
	v_readfirstlane_b32 s2, v176
	s_lshr_b32 s3, s2, 2
	s_lshl_b32 s3, s3, 3
	s_or_b32 s3, s3, s33
	s_and_b32 s2, s2, 3
	s_lshl_b32 s3, s3, 2
	s_or_b32 s5, s3, s2
	s_cmpk_lt_i32 s5, 0x3f0
	s_cselect_b64 s[2:3], -1, 0
	s_cmpk_gt_i32 s5, 0x3ef
	s_cselect_b64 s[18:19], -1, 0
	s_and_b64 vcc, exec, s[18:19]
	s_cbranch_vccnz .LBB0_1757
	s_mul_hi_i32 s4, s5, 0x38e38e39
	s_lshr_b32 s6, s4, 31
	s_ashr_i32 s4, s4, 6
	s_add_i32 s4, s4, s6
	s_lshl_b32 s6, s4, 3
	s_sub_i32 s7, 28, s6
	s_min_u32 s7, s7, 8
	v_cvt_f32_ubyte0_e32 v176, s7
	v_rcp_iflag_f32_e32 v176, v176
	s_sub_i32 s9, 0, s7
	s_mulk_i32 s4, 0xfee0
	s_add_i32 s4, s4, s5
	v_mul_f32_e32 v176, 0x4f7ffffe, v176
	v_cvt_u32_f32_e32 v176, v176
	s_abs_i32 s8, s4
	s_ashr_i32 s5, s4, 31
	v_readfirstlane_b32 s10, v176
	s_mul_i32 s9, s9, s10
	s_mul_hi_u32 s9, s10, s9
	s_add_i32 s10, s10, s9
	s_mul_hi_u32 s9, s8, s10
	s_mul_i32 s10, s9, s7
	s_sub_i32 s8, s8, s10
	s_add_i32 s10, s9, 1
	s_sub_i32 s11, s8, s7
	s_cmp_ge_u32 s8, s7
	s_cselect_b32 s9, s10, s9
	s_cselect_b32 s8, s11, s8
	s_add_i32 s10, s9, 1
	s_cmp_ge_u32 s8, s7
	s_cselect_b32 s8, s10, s9
	s_xor_b32 s8, s8, s5
	s_sub_i32 s5, s8, s5
	s_mul_i32 s7, s5, s7
	s_sub_i32 s4, s4, s7
	s_add_i32 s40, s4, s6
	s_lshl_b32 s4, s40, 8
	s_cmp_lt_i32 s40, 12
	s_cbranch_scc1 .LBB0_1759
	s_addk_i32 s4, 0xf400
	s_movk_i32 s6, 0x100
	s_mov_b64 s[20:21], 0xce80000
	s_mov_b64 s[10:11], 0x11280000
	s_mov_b64 s[12:13], 9
	s_branch .LBB0_1760

; DI int TID() { int t = threadIdx.x; asm volatile("" : "+v"(t)); return t; }
; DI void phase_gemm(const Params& p, int g, int kind, char* smem, float* rsl, int* s_item, int vlo, int vhi, int cslot) {
;     ...
;       __syncthreads();
;       if (TID() == 0) *s_item = atomicAdd(qctr, 1);
;       __syncthreads();
;       const int kq = *s_item;
;       const int tile = ((kq >> 6) * 8 + xcd) * 64 + (kq & 63);
;       if (tile >= total) { d.ok = false; return; }
;       const int strip = tile / (MT * 8), rem = tile - strip * (MT * 8);
;       const int wdt = min(8, nvt - strip * 8);
;       const int mt = rem / wdt, vt = vlo + strip * 8 + rem % wdt;
;       d.nt = kind == 0 ? nt_map0(vt) : vt; d.m0 = mt * 128; d.n0 = d.nt * 256;
;       if (kind == 0) { d.A = (const bfu*)(G + L0_H) + (long)d.m0 * 2048; d.Bt = P_WA + (long)d.n0 * 2048; d.K = 2048; }
;       else if (kind == 1) { d.A = (const bfu*)(G + L1_H) + (long)d.m0 * 2048; d.Bt = (const bfu*)((char*)P_WA + WA_W2) + (long)d.n0 * 2048; d.K = 2048; }
;       else if (kind == 2) {
;         if (d.nt < 12) { d.A = (const bfu*)(G + L1_QL) + (long)d.m0 * 512; d.Bt = (const bfu*)((char*)P_WA + WA_UQ) + (long)d.n0 * 512; d.K = 512; }
;         else { d.n0 -= 12 * 256; d.A = (const bfu*)(G + L1_KVL) + (long)d.m0 * 256; d.Bt = (const bfu*)((char*)P_WA + WA_UKV) + (long)d.n0 * 256; d.K = 256; }
;       } else {
;         const int layer = kind - 3;
;         if (layer == 1 && (d.m0 % T) < CTX) continue;
;         d.A = (const bfu*)(G + (layer == 0 ? L0_MIX : L1_MIX)) + (long)d.m0 * 4096;
.LBB0_2181:
	s_or_b64 exec, exec, s[2:3]
	s_waitcnt lgkmcnt(0)
	s_barrier
	ds_read_b32 v0, v204
	s_mov_b64 s[4:5], -1
	s_waitcnt lgkmcnt(0)
	v_readfirstlane_b32 s2, v0
	s_lshr_b32 s3, s2, 2
	s_lshl_b32 s3, s3, 3
	s_or_b32 s3, s3, s33
	s_and_b32 s2, s2, 3
	s_lshl_b32 s3, s3, 2
	s_or_b32 s10, s3, s2
	s_mov_b64 s[2:3], -1
	s_cmpk_gt_i32 s10, 0x11f
	s_cbranch_scc1 .LBB0_2176
	s_mul_hi_i32 s2, s10, 0x38e38e39
	s_lshr_b32 s3, s2, 31
	s_ashr_i32 s2, s2, 6
	s_add_i32 s6, s2, s3
	s_mul_i32 s2, s6, 0xfffffee0
	s_add_i32 s7, s2, s10
	s_ashr_i32 s2, s7, 31
	s_lshr_b32 s2, s2, 29
	s_add_i32 s2, s7, s2
	s_ashr_i32 s9, s2, 3
	s_lshl_b32 s8, s9, 7
	s_mul_hi_i32 s2, s8, 0x38e38e39
	s_lshr_b32 s3, s2, 31
	s_ashr_i32 s2, s2, 9
	s_add_i32 s2, s2, s3
	s_mulk_i32 s2, 0x900
	s_sub_i32 s4, s8, s2
	s_cmpk_gt_i32 s4, 0xff
	s_mov_b64 s[2:3], 0
	s_cselect_b64 s[4:5], -1, 0
	s_branch .LBB0_2176

; DI int TID() { int t = threadIdx.x; asm volatile("" : "+v"(t)); return t; }
; DI void phase_gemm(const Params& p, int g, int kind, char* smem, float* rsl, int* s_item, int vlo, int vhi, int cslot) {
;     ...
;       __syncthreads();
;       if (TID() == 0) *s_item = atomicAdd(qctr, 1);
;       __syncthreads();
;       const int kq = *s_item;
;       const int tile = ((kq >> 6) * 8 + xcd) * 64 + (kq & 63);
;       if (tile >= total) { d.ok = false; return; }
;       const int strip = tile / (MT * 8), rem = tile - strip * (MT * 8);
;       const int wdt = min(8, nvt - strip * 8);
;       const int mt = rem / wdt, vt = vlo + strip * 8 + rem % wdt;
;       d.nt = kind == 0 ? nt_map0(vt) : vt; d.m0 = mt * 128; d.n0 = d.nt * 256;
;       if (kind == 0) { d.A = (const bfu*)(G + L0_H) + (long)d.m0 * 2048; d.Bt = P_WA + (long)d.n0 * 2048; d.K = 2048; }
;       else if (kind == 1) { d.A = (const bfu*)(G + L1_H) + (long)d.m0 * 2048; d.Bt = (const bfu*)((char*)P_WA + WA_W2) + (long)d.n0 * 2048; d.K = 2048; }
;       else if (kind == 2) {
;         if (d.nt < 12) { d.A = (const bfu*)(G + L1_QL) + (long)d.m0 * 512; d.Bt = (const bfu*)((char*)P_WA + WA_UQ) + (long)d.n0 * 512; d.K = 512; }
;         else { d.n0 -= 12 * 256; d.A = (const bfu*)(G + L1_KVL) + (long)d.m0 * 256; d.Bt = (const bfu*)((char*)P_WA + WA_UKV) + (long)d.n0 * 256; d.K = 256; }
;       } else {
;         const int layer = kind - 3;
;         if (layer == 1 && (d.m0 % T) < CTX) continue;
;         d.A = (const bfu*)(G + (layer == 0 ? L0_MIX : L1_MIX)) + (long)d.m0 * 4096;
.LBB0_2193:
	s_or_b64 exec, exec, s[10:11]
	s_waitcnt lgkmcnt(0)
	s_barrier
	ds_read_b32 v176, v204
	s_mov_b64 s[14:15], -1
	s_mov_b64 s[16:17], -1
	s_waitcnt lgkmcnt(0)
	v_readfirstlane_b32 s7, v176
	s_lshr_b32 s9, s7, 2
	s_lshl_b32 s9, s9, 3
	s_or_b32 s9, s9, s33
	s_and_b32 s7, s7, 3
	s_lshl_b32 s9, s9, 2
	s_or_b32 s7, s9, s7
	s_cmpk_gt_i32 s7, 0x11f
	s_cbranch_scc1 .LBB0_2195
	s_mul_hi_i32 s9, s7, 0x38e38e39
	s_lshr_b32 s10, s9, 31
	s_ashr_i32 s9, s9, 6
	s_add_i32 s9, s9, s10
	s_mul_i32 s10, s9, 0xfffffee0
	s_add_i32 s7, s10, s7
	s_ashr_i32 s10, s7, 31
	s_lshr_b32 s10, s10, 29
	s_add_i32 s10, s7, s10
	s_and_b32 s11, s10, 0xfffff8
	s_sub_i32 s7, s7, s11
	s_lshl_b32 s10, s10, 4
	s_and_b32 s10, s10, 0xffffff80
	s_lshl_b32 s9, s9, 11
	s_lshl_b32 s7, s7, 8
	s_add_i32 s12, s9, s7
	s_mul_hi_i32 s7, s10, 0x38e38e39
	s_lshr_b32 s9, s7, 31
	s_ashr_i32 s7, s7, 9
	s_add_i32 s7, s7, s9
	s_mulk_i32 s7, 0x900
	s_sub_i32 s7, s10, s7
	s_cmpk_gt_i32 s7, 0xff
	s_mov_b64 s[14:15], 0
	s_cselect_b64 s[16:17], -1, 0
